# opt29: opt26 + tile sb+2's K LDS-DMA pair moved from after QK(a) to after QK(b)
# baseline (speedup 1.0000x reference)
.LBB0_889:
	s_add_i32 s6, s25, 0xffff8000
	s_and_b32 s6, s6, 0xc000
	s_add_i32 s27, s6, 0
	v_add_u32_e32 v80, s27, v199
	ds_read_b128 v[204:207], v80
	ds_read_b128 v[208:211], v80 offset:8192
	v_add_u32_e32 v80, s27, v200
	ds_read_b128 v[212:215], v80
	ds_read_b128 v[216:219], v80 offset:8192
	v_add_u32_e32 v80, s27, v201
	ds_read_b128 v[220:223], v80
	ds_read_b128 v[224:227], v80 offset:8192
	v_add_u32_e32 v80, s27, v202
	ds_read_b128 v[228:231], v80
	ds_read_b128 v[232:235], v80 offset:8192
	s_xor_b64 s[34:35], s[84:85], -1
	s_setprio 1
	s_waitcnt lgkmcnt(7)
	v_mfma_f32_32x32x16_bf16 v[80:95], v[204:207], v[140:143], v[64:79]
	s_waitcnt lgkmcnt(6)
	v_mfma_f32_32x32x16_bf16 v[64:79], v[208:211], v[140:143], v[64:79]
	s_waitcnt lgkmcnt(5)
	v_mfma_f32_32x32x16_bf16 v[80:95], v[212:215], v[136:139], v[80:95]
	s_waitcnt lgkmcnt(4)
	v_mfma_f32_32x32x16_bf16 v[64:79], v[216:219], v[136:139], v[64:79]
	s_waitcnt lgkmcnt(3)
	v_mfma_f32_32x32x16_bf16 v[80:95], v[220:223], v[132:135], v[80:95]
	s_waitcnt lgkmcnt(2)
	v_mfma_f32_32x32x16_bf16 v[64:79], v[224:227], v[132:135], v[64:79]
	s_waitcnt lgkmcnt(1)
	v_mfma_f32_32x32x16_bf16 v[80:95], v[228:231], v[128:131], v[80:95]
	s_waitcnt lgkmcnt(0)
	v_mfma_f32_32x32x16_bf16 v[64:79], v[232:235], v[128:131], v[64:79]
	s_setprio 0
	s_mov_b32 m0, s32
	s_nop 0
	global_load_lds_dwordx4 v164, s[98:99]
	s_add_i32 m0, s32, 0x400
	s_nop 0
	global_load_lds_dwordx4 v170, s[98:99]
	s_mov_b32 m0, s71
	s_nop 0
	global_load_lds_dwordx4 v168, s[100:101]
	s_add_i32 m0, s71, 0x400
	s_nop 0
	global_load_lds_dwordx4 v172, s[100:101]
	v_or_b32_e32 v174, s30, v187
	v_sub_u32_e32 v174, v188, v174
	v_cvt_f32_i32_e32 v174, v174
	s_mov_b64 s[6:7], -1
	s_and_b64 vcc, exec, s[34:35]
	s_cbranch_vccz .LBB0_895
	s_andn2_b64 vcc, exec, s[82:83]
	s_cbranch_vccnz .LBB0_892
	v_mul_f32_e64 v204, -s76, v174
	v_fma_f32 v205, -s76, v174, v194
	s_mov_b64 s[6:7], 0
